# adds gdn_prep S4b second pass: all LDS reads of a solve segment issued before its f32-MFMA chain
# baseline (speedup 1.0000x reference)
; #define LBAR() do { asm volatile("s_waitcnt lgkmcnt(0)" ::: "memory"); __builtin_amdgcn_s_barrier(); asm volatile("" ::: "memory"); } while (0)
;     ...
;     LBAR();
;     if (stop == 4) return;
;     {
;         const int g = lane >> 4, nn = lane & 15, cb = 16 * wid + nn;
; #pragma unroll
;         for (int blk = 0; blk < 4; ++blk) {
;             f32x4 acc;
; #pragma unroll
;             for (int r = 0; r < 4; ++r) acc[r] = rhs[(16 * blk + 4 * g + r) * 132 + cb];
; #pragma unroll
;             for (int k4 = 0; k4 < 4 * blk; ++k4) { const float av = -Lm[(4 * k4 + g) * 68 + 16 * blk + nn], bv = rhs[(4 * k4 + g) * 132 + cb];
;                 acc = __builtin_amdgcn_mfma_f32_16x16x4f32(av, bv, acc, 0, 0, 0); }
; #pragma unroll
;             for (int r = 0; r < 4; ++r) rhs[(16 * blk + 4 * g + r) * 132 + cb] = acc[r];
;             f32x4 xs = (f32x4){0.f, 0.f, 0.f, 0.f};
; #pragma unroll
;             for (int k4 = 0; k4 < 4; ++k4) { const float av = DIV[blk * 320 + nn * 20 + 4 * k4 + g], bv = rhs[(16 * blk + 4 * k4 + g) * 132 + cb];
;                 xs = __builtin_amdgcn_mfma_f32_16x16x4f32(av, bv, xs, 0, 0, 0); }
; #pragma unroll
;             for (int r = 0; r < 4; ++r) rhs[(16 * blk + 4 * g + r) * 132 + cb] = xs[r];
;         }
;     }
.LBB0_533:
	s_waitcnt lgkmcnt(0)
	s_barrier
	s_and_b64 vcc, exec, s[96:97]
	s_cbranch_vccz .LBB0_433
	ds_read_b32 v196, v184 offset:52288
	ds_read_b32 v197, v184 offset:53376
	ds_read_b32 v198, v184 offset:54464
	ds_read_b32 v199, v184 offset:55552
	ds_read_b32 v204, v184 offset:52352
	ds_read_b32 v205, v184 offset:53440
	ds_read_b32 v206, v184 offset:54528
	ds_read_b32 v207, v184 offset:55616
	ds_read_b32 v208, v184 offset:56704
	ds_read_b32 v209, v184 offset:57792
	ds_read_b32 v210, v184 offset:58880
	ds_read_b32 v211, v184 offset:59968
	ds_read_b32 v212, v184 offset:52416
	ds_read_b32 v213, v184 offset:53504
	ds_read_b32 v214, v184 offset:54592
	ds_read_b32 v215, v184 offset:55680
	ds_read_b32 v216, v184 offset:56768
	ds_read_b32 v217, v184 offset:57856
	ds_read_b32 v218, v184 offset:58944
	ds_read_b32 v219, v184 offset:60032
	ds_read_b32 v220, v184 offset:61120
	ds_read_b32 v221, v184 offset:62208
	ds_read_b32 v222, v184 offset:63296
	ds_read_b32 v223, v184 offset:64384
	ds_read2_b32 v[6:7], v168 offset1:4
	ds_read_b32 v224, v182
	ds_read_b32 v225, v182 offset:2112
	ds_read2_b32 v[226:227], v168 offset0:8 offset1:12
	ds_read_b32 v228, v182 offset:4224
	ds_read_b32 v229, v182 offset:6336
	s_waitcnt lgkmcnt(0)
	v_add_u32_e32 v9, 0x2400, v183
	v_add_u32_e32 v12, 0x400, v168
	v_add_u32_e32 v16, 0x800, v168
	v_readlane_b32 s42, v247, 35
	v_mfma_f32_16x16x4_f32 v[2:5], v6, v224, 0
	v_readlane_b32 s43, v247, 36
	s_andn2_b64 vcc, exec, s[42:43]
	v_mfma_f32_16x16x4_f32 v[2:5], v7, v225, v[2:5]
	v_mfma_f32_16x16x4_f32 v[2:5], v226, v228, v[2:5]
	v_add_u32_e32 v8, 0x400, v183
	v_mfma_f32_16x16x4_f32 v[2:5], v227, v229, v[2:5]
	s_nop 9
	ds_write2_b32 v183, v2, v3 offset1:132
	ds_write2_b32 v8, v4, v5 offset0:8 offset1:140
	v_add_u32_e32 v2, 0x2000, v183
	ds_read2_b32 v[4:5], v9 offset0:72 offset1:204
	ds_read2_b32 v[2:3], v2 offset0:64 offset1:196
	ds_read_b32 v8, v182
	ds_read_b32 v9, v182 offset:2112
	ds_read_b32 v10, v182 offset:4224
	ds_read_b32 v11, v182 offset:6336
	s_waitcnt lgkmcnt(0)
	v_xor_b32_e32 v6, 0x80000000, v196
	s_nop 1
	v_mfma_f32_16x16x4_f32 v[2:5], v6, v8, v[2:5]
	v_xor_b32_e32 v6, 0x80000000, v197
	s_nop 1
	v_mfma_f32_16x16x4_f32 v[2:5], v6, v9, v[2:5]
	v_xor_b32_e32 v6, 0x80000000, v198
	s_nop 1
	v_mfma_f32_16x16x4_f32 v[2:5], v6, v10, v[2:5]
	v_xor_b32_e32 v6, 0x80000000, v199
	s_nop 1
	v_mfma_f32_16x16x4_f32 v[2:5], v6, v11, v[2:5]
	s_nop 9
	ds_write_b32 v183, v2 offset:8448
	ds_write_b32 v183, v3 offset:8976
	ds_write_b32 v183, v4 offset:9504
	ds_write_b32 v183, v5 offset:10032
	ds_read2_b32 v[6:7], v12 offset0:64 offset1:68
	ds_read_b32 v224, v182 offset:8448
	ds_read_b32 v225, v182 offset:10560
	ds_read2_b32 v[226:227], v12 offset0:72 offset1:76
	ds_read_b32 v228, v182 offset:12672
	ds_read_b32 v229, v182 offset:14784
	s_waitcnt lgkmcnt(0)
	v_mfma_f32_16x16x4_f32 v[2:5], v6, v224, 0
	v_mfma_f32_16x16x4_f32 v[2:5], v7, v225, v[2:5]
	v_mfma_f32_16x16x4_f32 v[2:5], v226, v228, v[2:5]
	v_mfma_f32_16x16x4_f32 v[2:5], v227, v229, v[2:5]
	s_nop 9
	ds_write_b32 v183, v2 offset:8448
	ds_write_b32 v183, v3 offset:8976
	ds_write_b32 v183, v4 offset:9504
	ds_write_b32 v183, v5 offset:10032
	v_add_u32_e32 v2, 0x4200, v183
	v_add_u32_e32 v4, 0x4600, v183
	ds_read2_b32 v[2:3], v2 offset1:132
	ds_read2_b32 v[4:5], v4 offset0:8 offset1:140
	ds_read_b32 v12, v182 offset:8448
	ds_read_b32 v13, v182 offset:10560
	ds_read_b32 v14, v182 offset:12672
	ds_read_b32 v15, v182 offset:14784
	s_waitcnt lgkmcnt(0)
	v_xor_b32_e32 v6, 0x80000000, v204
	s_nop 1
	v_mfma_f32_16x16x4_f32 v[2:5], v6, v8, v[2:5]
	v_xor_b32_e32 v6, 0x80000000, v205
	s_nop 1
	v_mfma_f32_16x16x4_f32 v[2:5], v6, v9, v[2:5]
	v_xor_b32_e32 v6, 0x80000000, v206
	s_nop 1
	v_mfma_f32_16x16x4_f32 v[2:5], v6, v10, v[2:5]
	v_xor_b32_e32 v6, 0x80000000, v207
	s_nop 1
	v_mfma_f32_16x16x4_f32 v[2:5], v6, v11, v[2:5]
	v_xor_b32_e32 v6, 0x80000000, v208
	s_nop 1
	v_mfma_f32_16x16x4_f32 v[2:5], v6, v12, v[2:5]
	v_xor_b32_e32 v6, 0x80000000, v209
	s_nop 1
	v_mfma_f32_16x16x4_f32 v[2:5], v6, v13, v[2:5]
	v_xor_b32_e32 v6, 0x80000000, v210
	s_nop 1
	v_mfma_f32_16x16x4_f32 v[2:5], v6, v14, v[2:5]
	v_xor_b32_e32 v6, 0x80000000, v211
	s_nop 1
	v_mfma_f32_16x16x4_f32 v[2:5], v6, v15, v[2:5]
	s_nop 9
	ds_write_b32 v183, v2 offset:16896
	ds_write_b32 v183, v3 offset:17424
	ds_write_b32 v183, v4 offset:17952
	ds_write_b32 v183, v5 offset:18480
	ds_read2_b32 v[6:7], v16 offset0:128 offset1:132
	ds_read_b32 v224, v182 offset:16896
	ds_read_b32 v225, v182 offset:19008
	ds_read2_b32 v[226:227], v16 offset0:136 offset1:140
	ds_read_b32 v228, v182 offset:21120
	ds_read_b32 v229, v182 offset:23232
	s_waitcnt lgkmcnt(0)
; #define LAS __attribute__((address_space(3)))
; DI unsigned pk2(float lo, float hi) { typedef __bf16 b2 __attribute__((ext_vector_type(2))); f32x2 v = {lo, hi}; b2 b = __builtin_convertvector(v, b2); return __builtin_bit_cast(unsigned, b); }
;     ...
;     {
;         const int g = lane >> 4, nn = lane & 15, cb = 16 * wid + nn;
; #pragma unroll
;         for (int blk = 0; blk < 4; ++blk) {
;             f32x4 acc;
; #pragma unroll
;             for (int r = 0; r < 4; ++r) acc[r] = rhs[(16 * blk + 4 * g + r) * 132 + cb];
; #pragma unroll
;             for (int k4 = 0; k4 < 4 * blk; ++k4) { const float av = -Lm[(4 * k4 + g) * 68 + 16 * blk + nn], bv = rhs[(4 * k4 + g) * 132 + cb];
;                 acc = __builtin_amdgcn_mfma_f32_16x16x4f32(av, bv, acc, 0, 0, 0); }
; #pragma unroll
;             for (int r = 0; r < 4; ++r) rhs[(16 * blk + 4 * g + r) * 132 + cb] = acc[r];
;             f32x4 xs = (f32x4){0.f, 0.f, 0.f, 0.f};
; #pragma unroll
;             for (int k4 = 0; k4 < 4; ++k4) { const float av = DIV[blk * 320 + nn * 20 + 4 * k4 + g], bv = rhs[(16 * blk + 4 * k4 + g) * 132 + cb];
;                 xs = __builtin_amdgcn_mfma_f32_16x16x4f32(av, bv, xs, 0, 0, 0); }
; #pragma unroll
;             for (int r = 0; r < 4; ++r) rhs[(16 * blk + 4 * g + r) * 132 + cb] = xs[r];
;         }
;     }
;     LBAR();
;     if (stop == 5) return;
;     {
;         const int idx = tid; const int mt = idx >> 8, ks = (idx >> 6) & 3, ln = idx & 63, i = 32 * mt + (ln & 31), hh = ln >> 5, k0 = 16 * ks + 4 * hh;
;         const f32x4 a = *(const LAS f32x4*)(rhs + i * 132 + 64 + k0), bq = *(const LAS f32x4*)(rhs + i * 132 + 64 + k0 + 8);
;         u32x4 w; w.x = pk2(-a[0], -a[1]); w.y = pk2(-a[2], -a[3]); w.z = pk2(-bq[0], -bq[1]); w.w = pk2(-bq[2], -bq[3]);
;         *(u32x4*)(gout + idx * 16) = w;
;         const int tile = idx >> 7, ln2 = (idx >> 1) & 63, half = idx & 1, ct = tile >> 1, vt = tile & 1, vcol = 32 * vt + (ln2 & 31), h2 = ln2 >> 5;
;         float v[8];
; #pragma unroll
;         for (int e = 0; e < 8; ++e) { const int r = 8 * half + e; v[e] = rhs[(32 * ct + crow(r, h2)) * 132 + vcol]; }
;         u32x4 wu; wu.x = pk2(v[0], v[1]); wu.y = pk2(v[2], v[3]); wu.z = pk2(v[4], v[5]); wu.w = pk2(v[6], v[7]);
;         *(u32x4*)(gout + 4 * 8192 + idx * 16) = wu;
;         if (tid == 0) GL[item] = expf(glog);
	v_mfma_f32_16x16x4_f32 v[2:5], v6, v224, 0
	v_mfma_f32_16x16x4_f32 v[2:5], v7, v225, v[2:5]
	v_mfma_f32_16x16x4_f32 v[2:5], v226, v228, v[2:5]
	v_mfma_f32_16x16x4_f32 v[2:5], v227, v229, v[2:5]
	s_nop 9
	ds_write_b32 v183, v2 offset:16896
	ds_write_b32 v183, v3 offset:17424
	ds_write_b32 v183, v4 offset:17952
	ds_write_b32 v183, v5 offset:18480
	v_add_u32_e32 v2, 0x6200, v183
	v_add_u32_e32 v4, 0x6600, v183
	ds_read2_b32 v[2:3], v2 offset0:64 offset1:196
	ds_read2_b32 v[4:5], v4 offset0:72 offset1:204
	ds_read_b32 v224, v182 offset:16896
	ds_read_b32 v225, v182 offset:19008
	ds_read_b32 v226, v182 offset:21120
	ds_read_b32 v227, v182 offset:23232
	s_waitcnt lgkmcnt(0)
	v_xor_b32_e32 v6, 0x80000000, v212
	s_nop 1
	v_mfma_f32_16x16x4_f32 v[2:5], v6, v8, v[2:5]
	v_add_u32_e32 v8, 0xc00, v168
	v_xor_b32_e32 v6, 0x80000000, v213
	s_nop 1
	v_mfma_f32_16x16x4_f32 v[2:5], v6, v9, v[2:5]
	v_xor_b32_e32 v6, 0x80000000, v214
	s_nop 1
	v_mfma_f32_16x16x4_f32 v[2:5], v6, v10, v[2:5]
	v_xor_b32_e32 v6, 0x80000000, v215
	s_nop 1
	v_mfma_f32_16x16x4_f32 v[2:5], v6, v11, v[2:5]
	v_xor_b32_e32 v6, 0x80000000, v216
	s_nop 1
	v_mfma_f32_16x16x4_f32 v[2:5], v6, v12, v[2:5]
	v_xor_b32_e32 v6, 0x80000000, v217
	s_nop 1
	v_mfma_f32_16x16x4_f32 v[2:5], v6, v13, v[2:5]
	v_xor_b32_e32 v6, 0x80000000, v218
	s_nop 1
	v_mfma_f32_16x16x4_f32 v[2:5], v6, v14, v[2:5]
	v_xor_b32_e32 v6, 0x80000000, v219
	s_nop 1
	v_mfma_f32_16x16x4_f32 v[2:5], v6, v15, v[2:5]
	v_xor_b32_e32 v6, 0x80000000, v220
	s_nop 1
	v_mfma_f32_16x16x4_f32 v[2:5], v6, v224, v[2:5]
	v_xor_b32_e32 v6, 0x80000000, v221
	s_nop 1
	v_mfma_f32_16x16x4_f32 v[2:5], v6, v225, v[2:5]
	v_xor_b32_e32 v6, 0x80000000, v222
	s_nop 1
	v_mfma_f32_16x16x4_f32 v[2:5], v6, v226, v[2:5]
	v_xor_b32_e32 v6, 0x80000000, v223
	s_nop 1
	v_mfma_f32_16x16x4_f32 v[2:5], v6, v227, v[2:5]
	s_nop 9
	ds_write_b32 v183, v2 offset:25344
	ds_write_b32 v183, v3 offset:25872
	ds_write_b32 v183, v4 offset:26400
	ds_write_b32 v183, v5 offset:26928
	ds_read2_b32 v[6:7], v8 offset0:192 offset1:196
	ds_read_b32 v224, v182 offset:25344
	ds_read_b32 v225, v182 offset:27456
	ds_read2_b32 v[226:227], v8 offset0:200 offset1:204
	ds_read_b32 v228, v182 offset:29568
	ds_read_b32 v229, v182 offset:31680
	s_waitcnt lgkmcnt(0)
	v_mfma_f32_16x16x4_f32 v[2:5], v6, v224, 0
	v_mfma_f32_16x16x4_f32 v[2:5], v7, v225, v[2:5]
	v_mfma_f32_16x16x4_f32 v[2:5], v226, v228, v[2:5]
	v_mfma_f32_16x16x4_f32 v[2:5], v227, v229, v[2:5]
	s_nop 9
	ds_write_b32 v183, v2 offset:25344
	ds_write_b32 v183, v3 offset:25872
	ds_write_b32 v183, v4 offset:26400
	ds_write_b32 v183, v5 offset:26928
	s_waitcnt lgkmcnt(0)
	s_barrier
	s_cbranch_vccnz .LBB0_433
	ds_read_b128 v[2:5], v169 offset:256
	ds_read_b128 v[6:9], v169 offset:288
	s_waitcnt lgkmcnt(1)
	v_xor_b32_e32 v3, 0x80000000, v3
	v_xor_b32_e32 v2, 0x80000000, v2
	v_xor_b32_e32 v4, 0x80000000, v4
	v_xor_b32_e32 v5, 0x80000000, v5
	v_cvt_pk_bf16_f32 v2, v2, v3
	v_cvt_pk_bf16_f32 v3, v4, v5
	s_waitcnt lgkmcnt(0)
	v_xor_b32_e32 v4, 0x80000000, v7
	v_xor_b32_e32 v5, 0x80000000, v6
	v_cvt_pk_bf16_f32 v4, v5, v4
	v_xor_b32_e32 v5, 0x80000000, v8
	v_xor_b32_e32 v6, 0x80000000, v9
	ds_read_b32 v8, v185
	ds_read_b32 v9, v186
	ds_read_b32 v10, v187
	ds_read_b32 v11, v188
	ds_read_b32 v12, v189
	ds_read_b32 v13, v190
	ds_read_b32 v14, v191
	ds_read_b32 v15, v192
	v_cvt_pk_bf16_f32 v5, v5, v6
	v_lshl_add_u64 v[6:7], s[72:73], 0, v[90:91]
	global_store_dwordx4 v[6:7], v[2:5], off
	v_add_co_u32_e32 v6, vcc, 0x8000, v6
	s_waitcnt lgkmcnt(6)
	v_cvt_pk_bf16_f32 v2, v8, v9
	s_waitcnt lgkmcnt(4)
	v_cvt_pk_bf16_f32 v3, v10, v11
	s_waitcnt lgkmcnt(2)
	v_cvt_pk_bf16_f32 v4, v12, v13
	s_waitcnt lgkmcnt(0)
	v_cvt_pk_bf16_f32 v5, v14, v15
	v_addc_co_u32_e32 v7, vcc, 0, v7, vcc
	global_store_dwordx4 v[6:7], v[2:5], off
	s_and_saveexec_b64 s[42:43], s[86:87]
	s_cbranch_execz .LBB0_432
	v_mul_f32_e32 v2, 0x3fb8aa3b, v82
	v_rndne_f32_e32 v3, v2
	v_sub_f32_e32 v4, v2, v3
	v_fma_f32 v2, v82, s27, -v2
	v_fmac_f32_e32 v2, 0x32a5705f, v82
	v_add_f32_e32 v2, v4, v2
	v_exp_f32_e32 v2, v2
	v_cvt_i32_f32_e32 v3, v3
	s_lshl_b64 s[2:3], s[2:3], 2
	v_readlane_b32 s33, v247, 33
	v_cmp_ngt_f32_e32 vcc, s95, v82
	v_ldexp_f32 v2, v2, v3
	s_add_u32 s2, s33, s2
	v_readlane_b32 s33, v247, 34
	v_cndmask_b32_e32 v2, 0, v2, vcc
	v_cmp_nlt_f32_e32 vcc, s16, v82
	s_addc_u32 s3, s33, s3
	s_nop 0
	v_cndmask_b32_e32 v2, v193, v2, vcc
	global_store_dword v83, v2, s[2:3]
	s_branch .LBB0_432

; #define LBAR() do { asm volatile("s_waitcnt lgkmcnt(0)" ::: "memory"); __builtin_amdgcn_s_barrier(); asm volatile("" ::: "memory"); } while (0)
;     ...
;     LBAR();
;     if (stop == 4) return;
;     {
;         const int g = lane >> 4, nn = lane & 15, cb = 16 * wid + nn;
; #pragma unroll
;         for (int blk = 0; blk < 4; ++blk) {
;             f32x4 acc;
; #pragma unroll
;             for (int r = 0; r < 4; ++r) acc[r] = rhs[(16 * blk + 4 * g + r) * 132 + cb];
; #pragma unroll
;             for (int k4 = 0; k4 < 4 * blk; ++k4) { const float av = -Lm[(4 * k4 + g) * 68 + 16 * blk + nn], bv = rhs[(4 * k4 + g) * 132 + cb];
;                 acc = __builtin_amdgcn_mfma_f32_16x16x4f32(av, bv, acc, 0, 0, 0); }
; #pragma unroll
;             for (int r = 0; r < 4; ++r) rhs[(16 * blk + 4 * g + r) * 132 + cb] = acc[r];
;             f32x4 xs = (f32x4){0.f, 0.f, 0.f, 0.f};
; #pragma unroll
;             for (int k4 = 0; k4 < 4; ++k4) { const float av = DIV[blk * 320 + nn * 20 + 4 * k4 + g], bv = rhs[(16 * blk + 4 * k4 + g) * 132 + cb];
;                 xs = __builtin_amdgcn_mfma_f32_16x16x4f32(av, bv, xs, 0, 0, 0); }
; #pragma unroll
;             for (int r = 0; r < 4; ++r) rhs[(16 * blk + 4 * g + r) * 132 + cb] = xs[r];
;         }
;     }
.LBB0_1844:
	s_waitcnt lgkmcnt(0)
	s_barrier
	s_and_b64 vcc, exec, s[40:41]
	s_cbranch_vccz .LBB0_1744
	ds_read_b32 v196, v184 offset:52288
	ds_read_b32 v197, v184 offset:53376
	ds_read_b32 v198, v184 offset:54464
	ds_read_b32 v199, v184 offset:55552
	ds_read_b32 v204, v184 offset:52352
	ds_read_b32 v205, v184 offset:53440
	ds_read_b32 v206, v184 offset:54528
	ds_read_b32 v207, v184 offset:55616
	ds_read_b32 v208, v184 offset:56704
	ds_read_b32 v209, v184 offset:57792
	ds_read_b32 v210, v184 offset:58880
	ds_read_b32 v211, v184 offset:59968
	ds_read_b32 v212, v184 offset:52416
	ds_read_b32 v213, v184 offset:53504
	ds_read_b32 v214, v184 offset:54592
	ds_read_b32 v215, v184 offset:55680
	ds_read_b32 v216, v184 offset:56768
	ds_read_b32 v217, v184 offset:57856
	ds_read_b32 v218, v184 offset:58944
	ds_read_b32 v219, v184 offset:60032
	ds_read_b32 v220, v184 offset:61120
	ds_read_b32 v221, v184 offset:62208
	ds_read_b32 v222, v184 offset:63296
	ds_read_b32 v223, v184 offset:64384
	ds_read2_b32 v[6:7], v168 offset1:4
	ds_read_b32 v224, v182
	ds_read_b32 v225, v182 offset:2112
	ds_read2_b32 v[226:227], v168 offset0:8 offset1:12
	ds_read_b32 v228, v182 offset:4224
	ds_read_b32 v229, v182 offset:6336
	s_waitcnt lgkmcnt(0)
	v_add_u32_e32 v9, 0x2400, v183
	v_add_u32_e32 v12, 0x400, v168
	v_add_u32_e32 v16, 0x800, v168
	v_readlane_b32 s4, v247, 35
	v_mfma_f32_16x16x4_f32 v[2:5], v6, v224, 0
	v_readlane_b32 s5, v247, 36
	s_andn2_b64 vcc, exec, s[4:5]
	v_mfma_f32_16x16x4_f32 v[2:5], v7, v225, v[2:5]
	v_mfma_f32_16x16x4_f32 v[2:5], v226, v228, v[2:5]
	v_add_u32_e32 v8, 0x400, v183
	v_mfma_f32_16x16x4_f32 v[2:5], v227, v229, v[2:5]
	s_nop 9
	ds_write2_b32 v183, v2, v3 offset1:132
	ds_write2_b32 v8, v4, v5 offset0:8 offset1:140
	v_add_u32_e32 v2, 0x2000, v183
	ds_read2_b32 v[4:5], v9 offset0:72 offset1:204
	ds_read2_b32 v[2:3], v2 offset0:64 offset1:196
	ds_read_b32 v8, v182
	ds_read_b32 v9, v182 offset:2112
	ds_read_b32 v10, v182 offset:4224
	ds_read_b32 v11, v182 offset:6336
	s_waitcnt lgkmcnt(0)
	v_xor_b32_e32 v6, 0x80000000, v196
	s_nop 1
	v_mfma_f32_16x16x4_f32 v[2:5], v6, v8, v[2:5]
	v_xor_b32_e32 v6, 0x80000000, v197
	s_nop 1
	v_mfma_f32_16x16x4_f32 v[2:5], v6, v9, v[2:5]
	v_xor_b32_e32 v6, 0x80000000, v198
	s_nop 1
	v_mfma_f32_16x16x4_f32 v[2:5], v6, v10, v[2:5]
	v_xor_b32_e32 v6, 0x80000000, v199
	s_nop 1
	v_mfma_f32_16x16x4_f32 v[2:5], v6, v11, v[2:5]
	s_nop 9
	ds_write_b32 v183, v2 offset:8448
	ds_write_b32 v183, v3 offset:8976
	ds_write_b32 v183, v4 offset:9504
	ds_write_b32 v183, v5 offset:10032
	ds_read2_b32 v[6:7], v12 offset0:64 offset1:68
	ds_read_b32 v224, v182 offset:8448
	ds_read_b32 v225, v182 offset:10560
	ds_read2_b32 v[226:227], v12 offset0:72 offset1:76
	ds_read_b32 v228, v182 offset:12672
	ds_read_b32 v229, v182 offset:14784
	s_waitcnt lgkmcnt(0)
	v_mfma_f32_16x16x4_f32 v[2:5], v6, v224, 0
	v_mfma_f32_16x16x4_f32 v[2:5], v7, v225, v[2:5]
	v_mfma_f32_16x16x4_f32 v[2:5], v226, v228, v[2:5]
	v_mfma_f32_16x16x4_f32 v[2:5], v227, v229, v[2:5]
	s_nop 9
	ds_write_b32 v183, v2 offset:8448
	ds_write_b32 v183, v3 offset:8976
	ds_write_b32 v183, v4 offset:9504
	ds_write_b32 v183, v5 offset:10032
	v_add_u32_e32 v2, 0x4200, v183
	v_add_u32_e32 v4, 0x4600, v183
	ds_read2_b32 v[2:3], v2 offset1:132
	ds_read2_b32 v[4:5], v4 offset0:8 offset1:140
	ds_read_b32 v12, v182 offset:8448
	ds_read_b32 v13, v182 offset:10560
	ds_read_b32 v14, v182 offset:12672
	ds_read_b32 v15, v182 offset:14784
	s_waitcnt lgkmcnt(0)
	v_xor_b32_e32 v6, 0x80000000, v204
	s_nop 1
	v_mfma_f32_16x16x4_f32 v[2:5], v6, v8, v[2:5]
	v_xor_b32_e32 v6, 0x80000000, v205
	s_nop 1
	v_mfma_f32_16x16x4_f32 v[2:5], v6, v9, v[2:5]
	v_xor_b32_e32 v6, 0x80000000, v206
	s_nop 1
	v_mfma_f32_16x16x4_f32 v[2:5], v6, v10, v[2:5]
	v_xor_b32_e32 v6, 0x80000000, v207
	s_nop 1
	v_mfma_f32_16x16x4_f32 v[2:5], v6, v11, v[2:5]
	v_xor_b32_e32 v6, 0x80000000, v208
	s_nop 1
	v_mfma_f32_16x16x4_f32 v[2:5], v6, v12, v[2:5]
	v_xor_b32_e32 v6, 0x80000000, v209
	s_nop 1
	v_mfma_f32_16x16x4_f32 v[2:5], v6, v13, v[2:5]
	v_xor_b32_e32 v6, 0x80000000, v210
	s_nop 1
	v_mfma_f32_16x16x4_f32 v[2:5], v6, v14, v[2:5]
	v_xor_b32_e32 v6, 0x80000000, v211
	s_nop 1
	v_mfma_f32_16x16x4_f32 v[2:5], v6, v15, v[2:5]
	s_nop 9
	ds_write_b32 v183, v2 offset:16896
	ds_write_b32 v183, v3 offset:17424
	ds_write_b32 v183, v4 offset:17952
	ds_write_b32 v183, v5 offset:18480
	ds_read2_b32 v[6:7], v16 offset0:128 offset1:132
	ds_read_b32 v224, v182 offset:16896
	ds_read_b32 v225, v182 offset:19008
	ds_read2_b32 v[226:227], v16 offset0:136 offset1:140
	ds_read_b32 v228, v182 offset:21120
	ds_read_b32 v229, v182 offset:23232
	s_waitcnt lgkmcnt(0)
; #define LAS __attribute__((address_space(3)))
; DI unsigned pk2(float lo, float hi) { typedef __bf16 b2 __attribute__((ext_vector_type(2))); f32x2 v = {lo, hi}; b2 b = __builtin_convertvector(v, b2); return __builtin_bit_cast(unsigned, b); }
;     ...
;     {
;         const int g = lane >> 4, nn = lane & 15, cb = 16 * wid + nn;
; #pragma unroll
;         for (int blk = 0; blk < 4; ++blk) {
;             f32x4 acc;
; #pragma unroll
;             for (int r = 0; r < 4; ++r) acc[r] = rhs[(16 * blk + 4 * g + r) * 132 + cb];
; #pragma unroll
;             for (int k4 = 0; k4 < 4 * blk; ++k4) { const float av = -Lm[(4 * k4 + g) * 68 + 16 * blk + nn], bv = rhs[(4 * k4 + g) * 132 + cb];
;                 acc = __builtin_amdgcn_mfma_f32_16x16x4f32(av, bv, acc, 0, 0, 0); }
; #pragma unroll
;             for (int r = 0; r < 4; ++r) rhs[(16 * blk + 4 * g + r) * 132 + cb] = acc[r];
;             f32x4 xs = (f32x4){0.f, 0.f, 0.f, 0.f};
; #pragma unroll
;             for (int k4 = 0; k4 < 4; ++k4) { const float av = DIV[blk * 320 + nn * 20 + 4 * k4 + g], bv = rhs[(16 * blk + 4 * k4 + g) * 132 + cb];
;                 xs = __builtin_amdgcn_mfma_f32_16x16x4f32(av, bv, xs, 0, 0, 0); }
; #pragma unroll
;             for (int r = 0; r < 4; ++r) rhs[(16 * blk + 4 * g + r) * 132 + cb] = xs[r];
;         }
;     }
;     LBAR();
;     if (stop == 5) return;
;     {
;         const int idx = tid; const int mt = idx >> 8, ks = (idx >> 6) & 3, ln = idx & 63, i = 32 * mt + (ln & 31), hh = ln >> 5, k0 = 16 * ks + 4 * hh;
;         const f32x4 a = *(const LAS f32x4*)(rhs + i * 132 + 64 + k0), bq = *(const LAS f32x4*)(rhs + i * 132 + 64 + k0 + 8);
;         u32x4 w; w.x = pk2(-a[0], -a[1]); w.y = pk2(-a[2], -a[3]); w.z = pk2(-bq[0], -bq[1]); w.w = pk2(-bq[2], -bq[3]);
;         *(u32x4*)(gout + idx * 16) = w;
;         const int tile = idx >> 7, ln2 = (idx >> 1) & 63, half = idx & 1, ct = tile >> 1, vt = tile & 1, vcol = 32 * vt + (ln2 & 31), h2 = ln2 >> 5;
;         float v[8];
; #pragma unroll
;         for (int e = 0; e < 8; ++e) { const int r = 8 * half + e; v[e] = rhs[(32 * ct + crow(r, h2)) * 132 + vcol]; }
;         u32x4 wu; wu.x = pk2(v[0], v[1]); wu.y = pk2(v[2], v[3]); wu.z = pk2(v[4], v[5]); wu.w = pk2(v[6], v[7]);
;         *(u32x4*)(gout + 4 * 8192 + idx * 16) = wu;
;         if (tid == 0) GL[item] = expf(glog);
	v_mfma_f32_16x16x4_f32 v[2:5], v6, v224, 0
	v_mfma_f32_16x16x4_f32 v[2:5], v7, v225, v[2:5]
	v_mfma_f32_16x16x4_f32 v[2:5], v226, v228, v[2:5]
	v_mfma_f32_16x16x4_f32 v[2:5], v227, v229, v[2:5]
	s_nop 9
	ds_write_b32 v183, v2 offset:16896
	ds_write_b32 v183, v3 offset:17424
	ds_write_b32 v183, v4 offset:17952
	ds_write_b32 v183, v5 offset:18480
	v_add_u32_e32 v2, 0x6200, v183
	v_add_u32_e32 v4, 0x6600, v183
	ds_read2_b32 v[2:3], v2 offset0:64 offset1:196
	ds_read2_b32 v[4:5], v4 offset0:72 offset1:204
	ds_read_b32 v224, v182 offset:16896
	ds_read_b32 v225, v182 offset:19008
	ds_read_b32 v226, v182 offset:21120
	ds_read_b32 v227, v182 offset:23232
	s_waitcnt lgkmcnt(0)
	v_xor_b32_e32 v6, 0x80000000, v212
	s_nop 1
	v_mfma_f32_16x16x4_f32 v[2:5], v6, v8, v[2:5]
	v_add_u32_e32 v8, 0xc00, v168
	v_xor_b32_e32 v6, 0x80000000, v213
	s_nop 1
	v_mfma_f32_16x16x4_f32 v[2:5], v6, v9, v[2:5]
	v_xor_b32_e32 v6, 0x80000000, v214
	s_nop 1
	v_mfma_f32_16x16x4_f32 v[2:5], v6, v10, v[2:5]
	v_xor_b32_e32 v6, 0x80000000, v215
	s_nop 1
	v_mfma_f32_16x16x4_f32 v[2:5], v6, v11, v[2:5]
	v_xor_b32_e32 v6, 0x80000000, v216
	s_nop 1
	v_mfma_f32_16x16x4_f32 v[2:5], v6, v12, v[2:5]
	v_xor_b32_e32 v6, 0x80000000, v217
	s_nop 1
	v_mfma_f32_16x16x4_f32 v[2:5], v6, v13, v[2:5]
	v_xor_b32_e32 v6, 0x80000000, v218
	s_nop 1
	v_mfma_f32_16x16x4_f32 v[2:5], v6, v14, v[2:5]
	v_xor_b32_e32 v6, 0x80000000, v219
	s_nop 1
	v_mfma_f32_16x16x4_f32 v[2:5], v6, v15, v[2:5]
	v_xor_b32_e32 v6, 0x80000000, v220
	s_nop 1
	v_mfma_f32_16x16x4_f32 v[2:5], v6, v224, v[2:5]
	v_xor_b32_e32 v6, 0x80000000, v221
	s_nop 1
	v_mfma_f32_16x16x4_f32 v[2:5], v6, v225, v[2:5]
	v_xor_b32_e32 v6, 0x80000000, v222
	s_nop 1
	v_mfma_f32_16x16x4_f32 v[2:5], v6, v226, v[2:5]
	v_xor_b32_e32 v6, 0x80000000, v223
	s_nop 1
	v_mfma_f32_16x16x4_f32 v[2:5], v6, v227, v[2:5]
	s_nop 9
	ds_write_b32 v183, v2 offset:25344
	ds_write_b32 v183, v3 offset:25872
	ds_write_b32 v183, v4 offset:26400
	ds_write_b32 v183, v5 offset:26928
	ds_read2_b32 v[6:7], v8 offset0:192 offset1:196
	ds_read_b32 v224, v182 offset:25344
	ds_read_b32 v225, v182 offset:27456
	ds_read2_b32 v[226:227], v8 offset0:200 offset1:204
	ds_read_b32 v228, v182 offset:29568
	ds_read_b32 v229, v182 offset:31680
	s_waitcnt lgkmcnt(0)
	v_mfma_f32_16x16x4_f32 v[2:5], v6, v224, 0
	v_mfma_f32_16x16x4_f32 v[2:5], v7, v225, v[2:5]
	v_mfma_f32_16x16x4_f32 v[2:5], v226, v228, v[2:5]
	v_mfma_f32_16x16x4_f32 v[2:5], v227, v229, v[2:5]
	s_nop 9
	ds_write_b32 v183, v2 offset:25344
	ds_write_b32 v183, v3 offset:25872
	ds_write_b32 v183, v4 offset:26400
	ds_write_b32 v183, v5 offset:26928
	s_waitcnt lgkmcnt(0)
	s_barrier
	s_cbranch_vccnz .LBB0_1744
	ds_read_b128 v[2:5], v169 offset:256
	ds_read_b128 v[6:9], v169 offset:288
	s_waitcnt lgkmcnt(1)
	v_xor_b32_e32 v3, 0x80000000, v3
	v_xor_b32_e32 v2, 0x80000000, v2
	v_xor_b32_e32 v4, 0x80000000, v4
	v_xor_b32_e32 v5, 0x80000000, v5
	v_cvt_pk_bf16_f32 v2, v2, v3
	v_cvt_pk_bf16_f32 v3, v4, v5
	s_waitcnt lgkmcnt(0)
	v_xor_b32_e32 v4, 0x80000000, v7
	v_xor_b32_e32 v5, 0x80000000, v6
	v_cvt_pk_bf16_f32 v4, v5, v4
	v_xor_b32_e32 v5, 0x80000000, v8
	v_xor_b32_e32 v6, 0x80000000, v9
	ds_read_b32 v8, v185
	ds_read_b32 v9, v186
	ds_read_b32 v10, v187
	ds_read_b32 v11, v188
	ds_read_b32 v12, v189
	ds_read_b32 v13, v190
	ds_read_b32 v14, v191
	ds_read_b32 v15, v192
	v_cvt_pk_bf16_f32 v5, v5, v6
	v_lshl_add_u64 v[6:7], s[16:17], 0, v[90:91]
	global_store_dwordx4 v[6:7], v[2:5], off
	v_add_co_u32_e32 v6, vcc, 0x8000, v6
	s_waitcnt lgkmcnt(6)
	v_cvt_pk_bf16_f32 v2, v8, v9
	s_waitcnt lgkmcnt(4)
	v_cvt_pk_bf16_f32 v3, v10, v11
	s_waitcnt lgkmcnt(2)
	v_cvt_pk_bf16_f32 v4, v12, v13
	s_waitcnt lgkmcnt(0)
	v_cvt_pk_bf16_f32 v5, v14, v15
	v_addc_co_u32_e32 v7, vcc, 0, v7, vcc
	global_store_dwordx4 v[6:7], v[2:5], off
	s_and_saveexec_b64 s[16:17], s[86:87]
	s_cbranch_execz .LBB0_1743
	v_mul_f32_e32 v2, 0x3fb8aa3b, v82
	v_rndne_f32_e32 v3, v2
	v_sub_f32_e32 v4, v2, v3
	v_fma_f32 v2, v82, s2, -v2
	v_fmac_f32_e32 v2, 0x32a5705f, v82
	v_add_f32_e32 v2, v4, v2
	v_exp_f32_e32 v2, v2
	v_cvt_i32_f32_e32 v3, v3
	s_lshl_b64 s[26:27], s[68:69], 2
	v_readlane_b32 s4, v247, 33
	v_cmp_ngt_f32_e32 vcc, s3, v82
	v_ldexp_f32 v2, v2, v3
	s_add_u32 s26, s4, s26
	v_readlane_b32 s4, v247, 34
	v_cndmask_b32_e32 v2, 0, v2, vcc
	v_cmp_nlt_f32_e32 vcc, s64, v82
	s_addc_u32 s27, s4, s27
	s_nop 0
	v_cndmask_b32_e32 v2, v193, v2, vcc
	global_store_dword v83, v2, s[26:27]
	s_branch .LBB0_1743
